# full attention unit PV stage: last six V-fragment read pairs issued one step ahead into an alternate buffer pair (v[232:239]), VALU temp moved off the fragment buffer, counted lgkmcnt waits
# baseline (speedup 1.0000x reference)
; #define LAS __attribute__((address_space(3)))
; __device__ __forceinline__ void attn_unit(LAS unsigned char* lds, int unit, int mode, const bf16* QKVG, const float* sinks, const float* gain_a, bf16* MIX, float* SSA) {
;     ...
;     for (int i = i0; i < i1; ++i) {
;         const int inx = (i < 3) ? (i + 1) : 3;
; #pragma unroll
;         for (int k = 0; k < 4; ++k) qrow[k] = __builtin_nontemporal_load((const v4u*)(qrow0 + (size_t)(32 * inx + 8 * k) * QP));
; #pragma unroll
;         for (int k = 0; k < 4; ++k) grow[k] = __builtin_nontemporal_load((const v4u*)(grow0 + (size_t)(32 * i + 8 * k) * QP));
;         int qq = q - 4 * hh; asm volatile("" : "+v"(qq));
;         float base = slope2 * (float)(4 * hh); asm volatile("" : "+v"(base));
;         f32x16 st[5];
; #pragma unroll
;         for (int j = 0; j < 5; ++j) {
;             const bool tile_ok = !(nblk == 0 && (i + j) < 4);
;             const float sl = tile_ok ? slope2 : 0.f, bs = tile_ok ? base : -INFINITY;
; #pragma unroll
;             for (int r = 0; r < 16; ++r) st[j][r] = fmaf(sl, (float)((r & 3) + 8 * (r >> 2) + 32 * j), bs);
;         }
;         {
;             const LAS bf16* kp = Ks + (32 * i + q) * KP + hh * 8;
;             bf16x8 kf[2][5];
; #pragma unroll
;             for (int j = 0; j < 5; ++j) kf[0][j] = *(const LAS bf16x8*)(kp + j * 32 * KP);
; #pragma unroll
;             for (int s = 0; s < 4; ++s) {
;                 if (s < 3) {
; #pragma unroll
;                     for (int j = 0; j < 5; ++j) kf[(s + 1) & 1][j] = *(const LAS bf16x8*)(kp + j * 32 * KP + 16 * (s + 1));
;                 }
; #pragma unroll
;                 for (int j = 0; j < 5; ++j) st[j] = __builtin_amdgcn_mfma_f32_32x32x16_bf16(kf[s & 1][j], qr[s], st[j], 0, 0, 0);
;             }
;         }
.LBB0_296:
	s_waitcnt lgkmcnt(4)
	v_lshl_add_u64 v[0:1], v[112:113], 0, s[88:89]
	s_mov_b32 s6, 0x7800000
	v_add_co_u32_e64 v2, s[6:7], s6, v0
	s_cmp_lt_u32 s1, 3
	s_nop 0
	v_addc_co_u32_e64 v3, s[6:7], 0, v1, s[6:7]
	s_mov_b32 s6, 0x7809000
	s_nop 0
	v_add_co_u32_e64 v4, s[6:7], s6, v0
	s_cselect_b32 s94, s0, 0x60
	s_nop 0
	v_addc_co_u32_e64 v5, s[6:7], 0, v1, s[6:7]
	s_mov_b32 s6, 0x7812000
	s_nop 0
	v_add_co_u32_e64 v6, s[6:7], s6, v0
	v_mov_b32_e32 v152, v141
	s_nop 0
	v_addc_co_u32_e64 v7, s[6:7], 0, v1, s[6:7]
	s_mov_b32 s6, 0x781b000
	s_nop 0
	v_add_co_u32_e64 v0, s[6:7], s6, v0
	v_mov_b32_e32 v38, v142
	s_nop 0
	v_addc_co_u32_e64 v1, s[6:7], 0, v1, s[6:7]
	s_or_b32 s6, s94, 8
	s_nop 0
	v_mad_u64_u32 v[8:9], s[6:7], s6, v150, v[100:101]
	s_or_b32 s6, s94, 16
	s_nop 0
	v_mad_u64_u32 v[10:11], s[6:7], s6, v150, v[100:101]
	v_mad_u64_u32 v[12:13], s[6:7], s94, v150, v[100:101]
	s_or_b32 s6, s94, 24
	s_nop 0
	v_mad_u64_u32 v[14:15], s[6:7], s6, v150, v[100:101]
	ds_read_b128 v[82:85], v139 offset:96
	ds_read_b128 v[86:89], v139 offset:64
	ds_read_b128 v[94:97], v139
	ds_read_b128 v[90:93], v139 offset:32
	global_load_dwordx4 v[48:51], v[12:13], off nt
	global_load_dwordx4 v[52:55], v[8:9], off nt
	global_load_dwordx4 v[56:59], v[10:11], off nt
	global_load_dwordx4 v[60:63], v[14:15], off nt
	global_load_dwordx4 v[64:67], v[2:3], off offset:2560 nt
	global_load_dwordx4 v[68:71], v[4:5], off offset:2560 nt
	global_load_dwordx4 v[72:75], v[6:7], off offset:2560 nt
	global_load_dwordx4 v[76:79], v[0:1], off offset:2560 nt
	ds_read_b128 v[16:19], v145
	ds_read_b128 v[198:201], v145 offset:13824
	ds_read_b128 v[34:37], v145 offset:18432
	ds_read_b128 v[232:235], v145 offset:32
	ds_read_b128 v[236:239], v145 offset:18464
	v_cndmask_b32_e32 v14, v151, v38, vcc
	v_fma_f32 v0, 0, v106, v14
	v_add_f32_e32 v1, v106, v14
	v_pk_fma_f32 v[2:3], v[106:107], s[10:11], v[14:15] op_sel_hi:[1,1,0]
	v_pk_fma_f32 v[4:5], v[106:107], s[12:13], v[14:15] op_sel_hi:[1,1,0]
	v_pk_fma_f32 v[6:7], v[106:107], s[14:15], v[14:15] op_sel_hi:[1,1,0]
	v_pk_fma_f32 v[8:9], v[106:107], s[16:17], v[14:15] op_sel_hi:[1,1,0]
	v_pk_fma_f32 v[10:11], v[106:107], s[18:19], v[14:15] op_sel_hi:[1,1,0]
	v_pk_fma_f32 v[12:13], v[106:107], s[20:21], v[14:15] op_sel_hi:[1,1,0]
	v_pk_fma_f32 v[14:15], v[106:107], s[22:23], v[14:15] op_sel_hi:[1,1,0]
	v_mov_b32_e32 v105, v104
	v_pk_fma_f32 v[30:31], v[104:105], s[72:73], v[38:39] op_sel_hi:[1,1,0]
	s_waitcnt lgkmcnt(4)
	v_mfma_f32_32x32x16_bf16 v[0:15], v[16:19], v[94:97], v[0:15]
	v_fma_f32 v28, v104, s74, v38
	v_fma_f32 v29, v105, s75, v38
	v_fma_f32 v26, v104, s76, v38
	v_fma_f32 v27, v105, s77, v38
	v_fma_f32 v24, v104, s78, v38
	v_fma_f32 v25, v105, s79, v38
	v_pk_fma_f32 v[22:23], v[104:105], s[80:81], v[38:39] op_sel_hi:[1,1,0]
	v_pk_fma_f32 v[20:21], v[104:105], s[82:83], v[38:39] op_sel_hi:[1,1,0]
	v_pk_fma_f32 v[18:19], v[104:105], s[84:85], v[38:39] op_sel_hi:[1,1,0]
	v_pk_fma_f32 v[16:17], v[108:109], s[86:87], v[38:39] op_sel_hi:[1,1,0]
	s_cmp_gt_u32 s1, 2
	s_cselect_b64 s[6:7], -1, 0
	s_waitcnt lgkmcnt(2)
	v_mfma_f32_32x32x16_bf16 v[16:31], v[34:37], v[94:97], v[16:31]
	ds_read_b128 v[34:37], v145 offset:64
	s_or_b64 s[6:7], vcc, s[6:7]
	s_cmp_gt_u32 s1, 1
	v_cndmask_b32_e64 v32, 0, v104, s[6:7]
	v_cndmask_b32_e64 v132, v151, v38, s[6:7]
	s_cselect_b64 s[6:7], -1, 0
	s_or_b64 s[6:7], vcc, s[6:7]
	s_waitcnt lgkmcnt(2)
	v_mfma_f32_32x32x16_bf16 v[0:15], v[232:235], v[90:93], v[0:15]
	ds_read_b128 v[232:235], v145 offset:18496
	v_cndmask_b32_e64 v126, 0, v104, s[6:7]
	v_cndmask_b32_e64 v128, v151, v38, s[6:7]
	s_or_b32 s6, s1, s93
	s_cmp_eq_u32 s6, 0
	s_cselect_b64 s[6:7], -1, 0
	v_cndmask_b32_e64 v122, v104, 0, s[6:7]
	s_waitcnt lgkmcnt(2)
	v_mfma_f32_32x32x16_bf16 v[16:31], v[236:239], v[90:93], v[16:31]
	ds_read_b128 v[236:239], v145 offset:96
	v_cndmask_b32_e64 v124, v38, v151, s[6:7]
	v_cmp_gt_i32_e64 s[6:7], 0, v152
	v_fma_f32 v46, v32, s24, v132
	v_fma_f32 v47, v32, s25, v132
	v_pk_fma_f32 v[44:45], v[32:33], s[26:27], v[132:133] op_sel_hi:[0,1,0]
	v_pk_fma_f32 v[42:43], v[32:33], s[28:29], v[132:133] op_sel_hi:[0,1,0]
	v_pk_fma_f32 v[40:41], v[32:33], s[30:31], v[132:133] op_sel_hi:[0,1,0]
	s_waitcnt lgkmcnt(2)
	v_mfma_f32_32x32x16_bf16 v[0:15], v[34:37], v[86:89], v[0:15]
	ds_read_b128 v[34:37], v145 offset:18528
	v_fma_f32 v38, v32, s34, v132
	v_fma_f32 v39, v32, s35, v132
	s_waitcnt lgkmcnt(2)
	v_mfma_f32_32x32x16_bf16 v[16:31], v[232:235], v[86:89], v[16:31]
	s_waitcnt lgkmcnt(1)
	v_mfma_f32_32x32x16_bf16 v[0:15], v[236:239], v[82:85], v[0:15]
	s_waitcnt lgkmcnt(0)
; #define LAS __attribute__((address_space(3)))
; __device__ __forceinline__ void attn_unit(LAS unsigned char* lds, int unit, int mode, const bf16* QKVG, const float* sinks, const float* gain_a, bf16* MIX, float* SSA) {
;     ...
;         f32x16 st[5];
; #pragma unroll
;         for (int j = 0; j < 5; ++j) {
;             const bool tile_ok = !(nblk == 0 && (i + j) < 4);
;             const float sl = tile_ok ? slope2 : 0.f, bs = tile_ok ? base : -INFINITY;
; #pragma unroll
;             for (int r = 0; r < 16; ++r) st[j][r] = fmaf(sl, (float)((r & 3) + 8 * (r >> 2) + 32 * j), bs);
;         }
;         {
;             const LAS bf16* kp = Ks + (32 * i + q) * KP + hh * 8;
;             bf16x8 kf[2][5];
; #pragma unroll
;             for (int j = 0; j < 5; ++j) kf[0][j] = *(const LAS bf16x8*)(kp + j * 32 * KP);
; #pragma unroll
;             for (int s = 0; s < 4; ++s) {
;                 if (s < 3) {
; #pragma unroll
;                     for (int j = 0; j < 5; ++j) kf[(s + 1) & 1][j] = *(const LAS bf16x8*)(kp + j * 32 * KP + 16 * (s + 1));
;                 }
; #pragma unroll
;                 for (int j = 0; j < 5; ++j) st[j] = __builtin_amdgcn_mfma_f32_32x32x16_bf16(kf[s & 1][j], qr[s], st[j], 0, 0, 0);
;             }
;         }
;         const float sinkq = fmaf(slope2, (float)(128 + 4 * hh) + (float)qq, sink2);
;         float mx = sinkq;
; #pragma unroll
;         for (int r = 0; r < 16; ++r) {
;             const int cr = (r & 3) + 8 * (r >> 2);
;             const bool up = cr > qq;
;             st[0][r] = up ? st[0][r] : -INFINITY;
;             st[4][r] = up ? -INFINITY : st[4][r];
;         }
	v_mfma_f32_32x32x16_bf16 v[16:31], v[34:37], v[82:85], v[16:31]
	s_nop 8
	v_cndmask_b32_e64 v180, v151, v0, s[6:7]
	v_xor_b32_e32 v0, 32, v147
	v_fma_f32 v36, v32, s36, v132
	v_fma_f32 v37, v32, s37, v132
	v_fma_f32 v34, v32, s38, v132
	v_fma_f32 v35, v32, s39, v132
	v_pk_fma_f32 v[32:33], v[32:33], s[40:41], v[132:133] op_sel_hi:[0,1,0]
	v_cndmask_b32_e64 v179, v16, v151, s[6:7]
	v_cmp_gt_i32_e64 s[6:7], 1, v152
	s_nop 1
	v_cndmask_b32_e64 v184, v151, v1, s[6:7]
	v_cndmask_b32_e64 v175, v17, v151, s[6:7]
	v_cmp_gt_i32_e64 s[6:7], 2, v152
	v_and_b32_e32 v1, 64, v147
	v_add_u32_e32 v1, 64, v1
	v_cndmask_b32_e64 v188, v151, v2, s[6:7]
	v_cndmask_b32_e64 v176, v18, v151, s[6:7]
	v_cmp_gt_i32_e64 s[6:7], 3, v152
	v_pk_fma_f32 v[16:17], v[126:127], s[2:3], v[128:129] op_sel_hi:[0,1,0]
	s_nop 0
	v_cndmask_b32_e64 v192, v151, v3, s[6:7]
	v_cndmask_b32_e64 v178, v19, v151, s[6:7]
	v_cmp_gt_i32_e64 s[6:7], 8, v152
	v_pk_fma_f32 v[18:19], v[126:127], s[54:55], v[128:129] op_sel_hi:[0,1,0]
	s_nop 0
	v_cndmask_b32_e64 v181, v151, v4, s[6:7]
	v_cndmask_b32_e64 v177, v20, v151, s[6:7]
	v_cmp_gt_i32_e64 s[6:7], 9, v152
	s_nop 1
	v_cndmask_b32_e64 v185, v151, v5, s[6:7]
	v_cndmask_b32_e64 v174, v21, v151, s[6:7]
	v_cmp_gt_i32_e64 s[6:7], 10, v152
	v_pk_fma_f32 v[20:21], v[126:127], s[52:53], v[128:129] op_sel_hi:[0,1,0]
	s_nop 0
	v_cndmask_b32_e64 v189, v151, v6, s[6:7]
	v_cndmask_b32_e64 v173, v22, v151, s[6:7]
	v_cmp_gt_i32_e64 s[6:7], 11, v152
	s_nop 1
	v_cndmask_b32_e64 v193, v151, v7, s[6:7]
	v_cndmask_b32_e64 v158, v23, v151, s[6:7]
	v_cmp_gt_i32_e64 s[6:7], 16, v152
	ds_read_b128 v[4:7], v145 offset:9216
	v_pk_fma_f32 v[22:23], v[126:127], s[50:51], v[128:129] op_sel_hi:[0,1,0]
	v_cndmask_b32_e64 v182, v151, v8, s[6:7]
	v_cndmask_b32_e64 v172, v24, v151, s[6:7]
	v_cmp_gt_i32_e64 s[6:7], 17, v152
	s_nop 1
	v_cndmask_b32_e64 v186, v151, v9, s[6:7]
	v_cndmask_b32_e64 v159, v25, v151, s[6:7]
	v_cmp_gt_i32_e64 s[6:7], 18, v152
	v_pk_fma_f32 v[24:25], v[126:127], s[48:49], v[128:129] op_sel_hi:[0,1,0]
	v_pk_fma_f32 v[8:9], v[122:123], s[62:63], v[124:125] op_sel_hi:[0,1,0]
	v_cndmask_b32_e64 v190, v151, v10, s[6:7]
	v_cndmask_b32_e64 v157, v26, v151, s[6:7]
	v_cmp_gt_i32_e64 s[6:7], 19, v152
	s_nop 1
	v_cndmask_b32_e64 v194, v151, v11, s[6:7]
	v_cndmask_b32_e64 v156, v27, v151, s[6:7]
	v_cmp_gt_i32_e64 s[6:7], 24, v152
	v_pk_fma_f32 v[26:27], v[126:127], s[46:47], v[128:129] op_sel_hi:[0,1,0]
	v_pk_fma_f32 v[10:11], v[122:123], s[60:61], v[124:125] op_sel_hi:[0,1,0]
	v_cndmask_b32_e64 v183, v151, v12, s[6:7]
	v_cndmask_b32_e64 v105, v28, v151, s[6:7]
	v_cmp_gt_i32_e64 s[6:7], 25, v152
	s_nop 1
	v_cndmask_b32_e64 v187, v151, v13, s[6:7]
	v_cndmask_b32_e64 v153, v29, v151, s[6:7]
	v_cmp_gt_i32_e64 s[6:7], 26, v152
	v_pk_fma_f32 v[28:29], v[126:127], s[44:45], v[128:129] op_sel_hi:[0,1,0]
	v_pk_fma_f32 v[12:13], v[122:123], s[58:59], v[124:125] op_sel_hi:[0,1,0]
	v_cndmask_b32_e64 v191, v151, v14, s[6:7]
	v_cndmask_b32_e64 v155, v30, v151, s[6:7]
	v_cmp_gt_i32_e64 s[6:7], 27, v152
	s_nop 1
	v_cndmask_b32_e64 v195, v151, v15, s[6:7]
	v_cndmask_b32_e64 v154, v31, v151, s[6:7]
	v_cmp_lt_i32_e64 s[6:7], v0, v1
	v_pk_fma_f32 v[30:31], v[126:127], s[42:43], v[128:129] op_sel_hi:[0,1,0]
	v_pk_fma_f32 v[14:15], v[122:123], s[56:57], v[124:125] op_sel_hi:[0,1,0]
	v_cndmask_b32_e64 v196, v147, v0, s[6:7]
	v_add_u32_e32 v0, s0, v133
	v_subrev_u32_e32 v0, 32, v0
	v_ashrrev_i32_e32 v1, 31, v0
	v_lshlrev_b64 v[0:1], 12, v[0:1]
	v_lshl_add_u64 v[114:115], v[110:111], 0, v[0:1]
	ds_read_b128 v[0:3], v145 offset:4608
	s_waitcnt lgkmcnt(0)
	v_mfma_f32_32x32x16_bf16 v[32:47], v[0:3], v[94:97], v[32:47]
	v_fma_f32 v2, v122, s68, v124
	v_fma_f32 v3, v122, s69, v124
	v_fma_f32 v0, v122, s70, v124
	v_fma_f32 v1, v122, s71, v124
	s_mov_b32 s6, 0x8000
	v_add_co_u32_e64 v116, s[6:7], s6, v114
	s_nop 1
	v_addc_co_u32_e64 v117, s[6:7], 0, v115, s[6:7]
	v_mfma_f32_32x32x16_bf16 v[16:31], v[4:7], v[94:97], v[16:31]
	v_fma_f32 v6, v122, s64, v124
	v_fma_f32 v7, v122, s65, v124
	v_fma_f32 v4, v122, s66, v124
	v_fma_f32 v5, v122, s67, v124
	s_mov_b32 s6, 0x10000
	v_add_co_u32_e64 v118, s[6:7], s6, v114
	s_nop 1
	v_addc_co_u32_e64 v119, s[6:7], 0, v115, s[6:7]
	v_mfma_f32_32x32x16_bf16 v[0:15], v[198:201], v[94:97], v[0:15]
	ds_read_b128 v[94:97], v145 offset:4640
	ds_read_b128 v[232:235], v145 offset:9248
	ds_read_b128 v[236:239], v145 offset:13856
	s_mov_b32 s6, 0x18000
	v_add_co_u32_e64 v120, s[6:7], s6, v114
	s_nop 1
	v_addc_co_u32_e64 v121, s[6:7], 0, v115, s[6:7]
	s_waitcnt lgkmcnt(2)
	v_mfma_f32_32x32x16_bf16 v[32:47], v[94:97], v[90:93], v[32:47]
	ds_read_b128 v[94:97], v145 offset:4672
	s_waitcnt lgkmcnt(2)
	v_mfma_f32_32x32x16_bf16 v[16:31], v[232:235], v[90:93], v[16:31]
	ds_read_b128 v[232:235], v145 offset:9280
	s_waitcnt lgkmcnt(2)
	v_mfma_f32_32x32x16_bf16 v[0:15], v[236:239], v[90:93], v[0:15]
	ds_read_b128 v[236:239], v145 offset:13888
	s_waitcnt lgkmcnt(2)
	v_mfma_f32_32x32x16_bf16 v[32:47], v[94:97], v[86:89], v[32:47]
	ds_read_b128 v[94:97], v145 offset:4704
	s_waitcnt lgkmcnt(2)
	v_mfma_f32_32x32x16_bf16 v[16:31], v[232:235], v[86:89], v[16:31]
	ds_read_b128 v[232:235], v145 offset:9312
	s_waitcnt lgkmcnt(2)
	v_mfma_f32_32x32x16_bf16 v[0:15], v[236:239], v[86:89], v[0:15]
	ds_read_b128 v[236:239], v145 offset:13920
	v_cvt_f32_i32_e32 v90, v152
	v_add_f32_e32 v90, v143, v90
	s_waitcnt lgkmcnt(2)
	v_mfma_f32_32x32x16_bf16 v[32:47], v[94:97], v[82:85], v[32:47]
	s_waitcnt lgkmcnt(1)
	v_mfma_f32_32x32x16_bf16 v[16:31], v[232:235], v[82:85], v[16:31]
	s_waitcnt lgkmcnt(0)
; #define LAS __attribute__((address_space(3)))
; __device__ __forceinline__ unsigned pk2(float lo, float hi) { return pg8::cvt_pk_bf16(lo, hi); }
; __device__ __forceinline__ void attn_unit(LAS unsigned char* lds, int unit, int mode, const bf16* QKVG, const float* sinks, const float* gain_a, bf16* MIX, float* SSA) {
;     ...
; #pragma unroll
;         for (int j = 0; j < 5; ++j)
; #pragma unroll
;             for (int r = 0; r < 16; ++r) mx = fmaxf(mx, st[j][r]);
;         mx = fmaxf(mx, __shfl_xor(mx, 32));
;         float sum = 0.f;
; #pragma unroll
;         for (int j = 0; j < 5; ++j)
; #pragma unroll
;             for (int r = 0; r < 16; ++r) { const float p = __builtin_amdgcn_exp2f(st[j][r] - mx); st[j][r] = p; sum += p; }
;         sum += __shfl_xor(sum, 32);
;         sum += __builtin_amdgcn_exp2f(sinkq - mx);
;         const float inv = __builtin_amdgcn_rcpf(sum);
;         f32x16 ot[2]; ot[0] = f32x16{}; ot[1] = f32x16{};
; #pragma unroll
;         for (int j = 0; j < 5; ++j)
; #pragma unroll
;             for (int s2 = 0; s2 < 2; ++s2) {
;                 v4u pw; pw.x = pk2(st[j][8 * s2 + 0], st[j][8 * s2 + 1]); pw.y = pk2(st[j][8 * s2 + 2], st[j][8 * s2 + 3]);
;                 pw.z = pk2(st[j][8 * s2 + 4], st[j][8 * s2 + 5]); pw.w = pk2(st[j][8 * s2 + 6], st[j][8 * s2 + 7]);
;                 const bf16x8 pf = __builtin_bit_cast(bf16x8, pw);
; #pragma unroll
;                 for (int db = 0; db < 2; ++db) {
;                     const bf16x8 vf = *(const LAS bf16x8*)(Vt + (db * 32 + q) * VP + 32 * (i + j) + 16 * s2 + 8 * hh);
;                     ot[db] = __builtin_amdgcn_mfma_f32_32x32x16_bf16(vf, pf, ot[db], 0, 0, 0);
;                 }
;             }
	v_mfma_f32_32x32x16_bf16 v[0:15], v[236:239], v[82:85], v[0:15]
	v_fma_f32 v83, v104, v90, v140
	v_max3_f32 v82, v83, v180, v184
	v_max3_f32 v82, v82, v188, v192
	v_max3_f32 v82, v82, v181, v185
	v_max3_f32 v82, v82, v189, v193
	v_max3_f32 v82, v82, v182, v186
	v_max3_f32 v82, v82, v190, v194
	v_max3_f32 v82, v82, v183, v187
	v_max3_f32 v82, v82, v191, v195
	v_max3_f32 v82, v82, v32, v33
	v_max3_f32 v82, v82, v34, v35
	v_max3_f32 v82, v82, v36, v37
	v_max3_f32 v82, v82, v38, v39
	v_max3_f32 v82, v82, v40, v41
	v_max3_f32 v82, v82, v42, v43
	v_max3_f32 v82, v82, v44, v45
	v_max3_f32 v82, v82, v46, v47
	v_max3_f32 v82, v82, v16, v17
	v_max3_f32 v82, v82, v18, v19
	v_max3_f32 v82, v82, v20, v21
	v_max3_f32 v82, v82, v22, v23
	v_max3_f32 v82, v82, v24, v25
	v_max3_f32 v82, v82, v26, v27
	v_max3_f32 v82, v82, v28, v29
	v_max3_f32 v82, v82, v30, v31
	v_max3_f32 v82, v82, v0, v1
	v_max3_f32 v82, v82, v2, v3
	v_max3_f32 v82, v82, v4, v5
	v_max3_f32 v82, v82, v6, v7
	v_max3_f32 v82, v82, v8, v9
	v_max3_f32 v82, v82, v10, v11
	v_max3_f32 v82, v82, v12, v13
	v_max3_f32 v82, v82, v14, v15
	v_max3_f32 v82, v82, v179, v175
	v_max3_f32 v82, v82, v176, v178
	v_max3_f32 v82, v82, v177, v174
	v_max3_f32 v82, v82, v173, v158
	v_max3_f32 v82, v82, v172, v159
	v_max3_f32 v82, v82, v157, v156
	v_max3_f32 v82, v82, v105, v153
	v_max3_f32 v84, v82, v155, v154
	v_lshlrev_b32_e32 v82, 2, v196
	ds_bpermute_b32 v85, v82, v84
	s_waitcnt lgkmcnt(0)
	v_max_f32_e32 v85, v85, v85
	v_max_f32_e32 v92, v84, v85
	v_sub_f32_e32 v84, v180, v92
	v_exp_f32_e32 v84, v84
	v_sub_f32_e32 v85, v184, v92
	v_exp_f32_e32 v85, v85
	v_sub_f32_e32 v86, v188, v92
	v_exp_f32_e32 v86, v86
	v_sub_f32_e32 v87, v192, v92
	v_exp_f32_e32 v87, v87
	v_sub_f32_e32 v89, v181, v92
	v_add_f32_e32 v88, 0, v84
	v_exp_f32_e32 v89, v89
	v_sub_f32_e32 v90, v185, v92
	v_add_f32_e32 v88, v85, v88
	v_exp_f32_e32 v90, v90
	v_sub_f32_e32 v91, v189, v92
	v_add_f32_e32 v88, v86, v88
	v_exp_f32_e32 v91, v91
	v_sub_f32_e32 v93, v193, v92
	v_add_f32_e32 v88, v87, v88
	v_exp_f32_e32 v93, v93
	v_sub_f32_e32 v94, v182, v92
	v_add_f32_e32 v88, v89, v88
	v_exp_f32_e32 v94, v94
	v_sub_f32_e32 v95, v186, v92
	v_add_f32_e32 v88, v90, v88
	v_exp_f32_e32 v95, v95
	v_sub_f32_e32 v96, v190, v92
	v_add_f32_e32 v88, v91, v88
	v_exp_f32_e32 v96, v96
	v_sub_f32_e32 v97, v194, v92
	v_add_f32_e32 v88, v93, v88
	v_exp_f32_e32 v97, v97
	v_sub_f32_e32 v122, v183, v92
	v_add_f32_e32 v88, v94, v88
	v_exp_f32_e32 v122, v122
	v_sub_f32_e32 v124, v187, v92
	v_add_f32_e32 v88, v95, v88
	v_exp_f32_e32 v124, v124
	v_sub_f32_e32 v126, v191, v92
	v_add_f32_e32 v88, v96, v88
	v_exp_f32_e32 v126, v126
	v_sub_f32_e32 v128, v195, v92
	v_add_f32_e32 v88, v97, v88
	v_exp_f32_e32 v128, v128
	v_sub_f32_e32 v32, v32, v92
	v_add_f32_e32 v88, v122, v88
	v_exp_f32_e32 v132, v32
	v_sub_f32_e32 v32, v33, v92
	v_add_f32_e32 v88, v124, v88
	v_exp_f32_e32 v152, v32
	v_sub_f32_e32 v32, v34, v92
	v_add_f32_e32 v88, v126, v88
	v_exp_f32_e32 v180, v32
	v_sub_f32_e32 v32, v35, v92
	v_add_f32_e32 v88, v128, v88
	v_exp_f32_e32 v181, v32
	v_sub_f32_e32 v33, v36, v92
	v_add_f32_e32 v32, v132, v88
	v_exp_f32_e32 v182, v33
	v_sub_f32_e32 v33, v37, v92
	v_add_f32_e32 v32, v152, v32
	v_exp_f32_e32 v183, v33
	v_sub_f32_e32 v33, v38, v92
	v_add_f32_e32 v32, v180, v32
	v_exp_f32_e32 v184, v33
	v_sub_f32_e32 v33, v39, v92
	v_add_f32_e32 v32, v181, v32
	v_exp_f32_e32 v185, v33
	v_sub_f32_e32 v33, v40, v92
	v_add_f32_e32 v32, v182, v32
	v_exp_f32_e32 v186, v33
	v_sub_f32_e32 v33, v41, v92
	v_add_f32_e32 v32, v183, v32
	v_exp_f32_e32 v187, v33
	v_sub_f32_e32 v33, v42, v92
	v_add_f32_e32 v32, v184, v32
	v_exp_f32_e32 v188, v33
	v_sub_f32_e32 v33, v43, v92
	v_add_f32_e32 v32, v185, v32
	v_exp_f32_e32 v189, v33
	v_sub_f32_e32 v33, v44, v92
	v_add_f32_e32 v32, v186, v32
	v_exp_f32_e32 v190, v33
	v_sub_f32_e32 v33, v45, v92
	v_add_f32_e32 v32, v187, v32
	v_exp_f32_e32 v191, v33
	v_sub_f32_e32 v33, v46, v92
	v_add_f32_e32 v32, v188, v32
	v_exp_f32_e32 v192, v33
	v_sub_f32_e32 v33, v47, v92
	v_add_f32_e32 v32, v189, v32
	v_exp_f32_e32 v193, v33
	v_sub_f32_e32 v16, v16, v92
	v_add_f32_e32 v32, v190, v32
	v_exp_f32_e32 v194, v16
	v_sub_f32_e32 v16, v17, v92
	v_add_f32_e32 v32, v191, v32
	v_exp_f32_e32 v195, v16
	v_sub_f32_e32 v16, v18, v92
	v_add_f32_e32 v32, v192, v32
	v_exp_f32_e32 v196, v16
	v_sub_f32_e32 v16, v19, v92
	v_add_f32_e32 v32, v193, v32
	v_exp_f32_e32 v197, v16
	v_sub_f32_e32 v17, v20, v92
	v_add_f32_e32 v16, v194, v32
	v_exp_f32_e32 v198, v17
	v_sub_f32_e32 v17, v21, v92
	v_add_f32_e32 v16, v195, v16
	v_exp_f32_e32 v199, v17
	v_sub_f32_e32 v17, v22, v92
	v_add_f32_e32 v16, v196, v16
	v_exp_f32_e32 v200, v17
	v_sub_f32_e32 v17, v23, v92
	v_add_f32_e32 v16, v197, v16
	v_exp_f32_e32 v201, v17
	v_sub_f32_e32 v17, v24, v92
	v_add_f32_e32 v16, v198, v16
	v_exp_f32_e32 v202, v17
	v_sub_f32_e32 v17, v25, v92
	v_add_f32_e32 v16, v199, v16
	v_exp_f32_e32 v203, v17
	v_sub_f32_e32 v17, v26, v92
	v_add_f32_e32 v16, v200, v16
	v_exp_f32_e32 v204, v17
	v_sub_f32_e32 v17, v27, v92
	v_add_f32_e32 v16, v201, v16
	v_exp_f32_e32 v205, v17
	v_sub_f32_e32 v17, v28, v92
	v_add_f32_e32 v16, v202, v16
	v_exp_f32_e32 v206, v17
	v_sub_f32_e32 v17, v29, v92
	v_add_f32_e32 v16, v203, v16
	v_exp_f32_e32 v207, v17
	v_sub_f32_e32 v17, v30, v92
	v_add_f32_e32 v16, v204, v16
	v_exp_f32_e32 v208, v17
	v_sub_f32_e32 v17, v31, v92
	v_add_f32_e32 v16, v205, v16
	v_exp_f32_e32 v209, v17
	v_sub_f32_e32 v0, v0, v92
	v_add_f32_e32 v16, v206, v16
	v_exp_f32_e32 v210, v0
	v_sub_f32_e32 v0, v1, v92
	v_add_f32_e32 v16, v207, v16
	v_exp_f32_e32 v211, v0
	v_sub_f32_e32 v0, v2, v92
	v_add_f32_e32 v16, v208, v16
	v_exp_f32_e32 v212, v0
	v_sub_f32_e32 v0, v3, v92
	v_add_f32_e32 v16, v209, v16
	v_exp_f32_e32 v213, v0
	v_add_f32_e32 v0, v210, v16
	v_add_f32_e32 v0, v211, v0
	v_add_f32_e32 v0, v212, v0
	v_add_f32_e32 v20, v213, v0
	v_sub_f32_e32 v0, v4, v92
	v_exp_f32_e32 v214, v0
	v_sub_f32_e32 v0, v5, v92
	v_exp_f32_e32 v215, v0
	v_sub_f32_e32 v0, v6, v92
	v_exp_f32_e32 v216, v0
	v_add_f32_e32 v4, v214, v20
	v_add_f32_e32 v4, v215, v4
	v_cvt_pk_bf16_f32 v0, v84, v85
	v_add_f32_e32 v20, v216, v4
	v_sub_f32_e32 v4, v7, v92
	v_cvt_pk_bf16_f32 v1, v86, v87
	v_cvt_pk_bf16_f32 v2, v89, v90
	v_cvt_pk_bf16_f32 v3, v91, v93
	v_exp_f32_e32 v93, v4
	v_sub_f32_e32 v4, v8, v92
	ds_read_b128 v[16:19], v99
	v_exp_f32_e32 v217, v4
	ds_read_b128 v[4:7], v99 offset:16896
	s_waitcnt lgkmcnt(1)
; #define LAS __attribute__((address_space(3)))
; __device__ __forceinline__ unsigned pk2(float lo, float hi) { return pg8::cvt_pk_bf16(lo, hi); }
; __device__ __forceinline__ void attn_unit(LAS unsigned char* lds, int unit, int mode, const bf16* QKVG, const float* sinks, const float* gain_a, bf16* MIX, float* SSA) {
;     ...
;         float sum = 0.f;
; #pragma unroll
;         for (int j = 0; j < 5; ++j)
; #pragma unroll
;             for (int r = 0; r < 16; ++r) { const float p = __builtin_amdgcn_exp2f(st[j][r] - mx); st[j][r] = p; sum += p; }
;         sum += __shfl_xor(sum, 32);
;         sum += __builtin_amdgcn_exp2f(sinkq - mx);
;         const float inv = __builtin_amdgcn_rcpf(sum);
;         f32x16 ot[2]; ot[0] = f32x16{}; ot[1] = f32x16{};
; #pragma unroll
;         for (int j = 0; j < 5; ++j)
; #pragma unroll
;             for (int s2 = 0; s2 < 2; ++s2) {
;                 v4u pw; pw.x = pk2(st[j][8 * s2 + 0], st[j][8 * s2 + 1]); pw.y = pk2(st[j][8 * s2 + 2], st[j][8 * s2 + 3]);
;                 pw.z = pk2(st[j][8 * s2 + 4], st[j][8 * s2 + 5]); pw.w = pk2(st[j][8 * s2 + 6], st[j][8 * s2 + 7]);
;                 const bf16x8 pf = __builtin_bit_cast(bf16x8, pw);
; #pragma unroll
;                 for (int db = 0; db < 2; ++db) {
;                     const bf16x8 vf = *(const LAS bf16x8*)(Vt + (db * 32 + q) * VP + 32 * (i + j) + 16 * s2 + 8 * hh);
;                     ot[db] = __builtin_amdgcn_mfma_f32_32x32x16_bf16(vf, pf, ot[db], 0, 0, 0);
;                 }
;             }
	v_mfma_f32_32x32x16_bf16 v[32:47], v[16:19], v[0:3], 0
	v_add_f32_e32 v8, v93, v20
	v_cvt_pk_bf16_f32 v84, v94, v95
	v_cvt_pk_bf16_f32 v85, v96, v97
	v_cvt_pk_bf16_f32 v86, v122, v124
	v_cvt_pk_bf16_f32 v87, v126, v128
	ds_read_b128 v[88:91], v99 offset:32
	v_add_f32_e32 v218, v217, v8
	s_waitcnt lgkmcnt(1)
	v_mfma_f32_32x32x16_bf16 v[16:31], v[4:7], v[0:3], 0
	v_sub_f32_e32 v0, v9, v92
	v_exp_f32_e32 v94, v0
	v_sub_f32_e32 v0, v10, v92
	v_exp_f32_e32 v95, v0
	v_sub_f32_e32 v0, v11, v92
	v_exp_f32_e32 v96, v0
	ds_read_b128 v[0:3], v99 offset:16928
	v_sub_f32_e32 v4, v12, v92
	s_waitcnt lgkmcnt(1)
	v_mfma_f32_32x32x16_bf16 v[32:47], v[88:91], v[84:87], v[32:47]
	v_exp_f32_e32 v88, v4
	v_cvt_pk_bf16_f32 v4, v132, v152
	v_cvt_pk_bf16_f32 v5, v180, v181
	v_cvt_pk_bf16_f32 v6, v182, v183
	v_cvt_pk_bf16_f32 v7, v184, v185
	ds_read_b128 v[8:11], v99 offset:64
	s_waitcnt lgkmcnt(1)
	v_mfma_f32_32x32x16_bf16 v[16:31], v[0:3], v[84:87], v[16:31]
	v_add_f32_e32 v0, v94, v218
	v_add_f32_e32 v0, v95, v0
	v_add_f32_e32 v0, v96, v0
	v_add_f32_e32 v12, v88, v0
	v_sub_f32_e32 v0, v13, v92
	v_exp_f32_e32 v89, v0
	ds_read_b128 v[0:3], v99 offset:16960
	s_waitcnt lgkmcnt(1)
	v_mfma_f32_32x32x16_bf16 v[32:47], v[8:11], v[4:7], v[32:47]
	v_sub_f32_e32 v8, v14, v92
	v_exp_f32_e32 v90, v8
	v_cvt_pk_bf16_f32 v8, v186, v187
	v_cvt_pk_bf16_f32 v9, v188, v189
	v_cvt_pk_bf16_f32 v10, v190, v191
	v_cvt_pk_bf16_f32 v11, v192, v193
	ds_read_b128 v[84:87], v99 offset:96
	s_waitcnt lgkmcnt(1)
	v_mfma_f32_32x32x16_bf16 v[16:31], v[0:3], v[4:7], v[16:31]
	v_add_f32_e32 v0, v89, v12
	v_add_f32_e32 v4, v90, v0
	v_sub_f32_e32 v0, v15, v92
	v_exp_f32_e32 v91, v0
	v_sub_f32_e32 v0, v179, v92
	v_exp_f32_e32 v97, v0
	ds_read_b128 v[0:3], v99 offset:16992
	s_waitcnt lgkmcnt(0)
	v_mfma_f32_32x32x16_bf16 v[16:31], v[0:3], v[8:11], v[16:31]
	v_sub_f32_e32 v0, v175, v92
	v_add_f32_e32 v4, v91, v4
	v_mfma_f32_32x32x16_bf16 v[32:47], v[84:87], v[8:11], v[32:47]
	v_exp_f32_e32 v85, v0
	v_sub_f32_e32 v0, v176, v92
	v_exp_f32_e32 v86, v0
	v_sub_f32_e32 v0, v178, v92
	v_add_f32_e32 v84, v97, v4
	v_cvt_pk_bf16_f32 v4, v194, v195
	v_cvt_pk_bf16_f32 v5, v196, v197
	v_cvt_pk_bf16_f32 v6, v198, v199
	v_cvt_pk_bf16_f32 v7, v200, v201
	ds_read_b128 v[12:15], v99 offset:128
	v_exp_f32_e32 v87, v0
	ds_read_b128 v[0:3], v99 offset:17024
	v_sub_f32_e32 v8, v177, v92
	v_exp_f32_e32 v122, v8
	ds_read_b128 v[232:235], v99 offset:160
	ds_read_b128 v[236:239], v99 offset:17056
	s_waitcnt lgkmcnt(2)
	v_mfma_f32_32x32x16_bf16 v[16:31], v[0:3], v[4:7], v[16:31]
	v_add_f32_e32 v240, v85, v84
	v_add_f32_e32 v240, v86, v240
	v_add_f32_e32 v240, v87, v240
	v_add_f32_e32 v84, v122, v240
	v_sub_f32_e32 v240, v174, v92
	v_cvt_pk_bf16_f32 v8, v202, v203
	v_cvt_pk_bf16_f32 v9, v204, v205
	v_mfma_f32_32x32x16_bf16 v[32:47], v[12:15], v[4:7], v[32:47]
	v_cvt_pk_bf16_f32 v10, v206, v207
	v_cvt_pk_bf16_f32 v11, v208, v209
	v_exp_f32_e32 v124, v240
	v_sub_f32_e32 v4, v173, v92
	v_exp_f32_e32 v126, v4
	ds_read_b128 v[12:15], v99 offset:192
	ds_read_b128 v[0:3], v99 offset:17088
	s_waitcnt lgkmcnt(2)
	v_mfma_f32_32x32x16_bf16 v[16:31], v[236:239], v[8:11], v[16:31]
	v_add_f32_e32 v240, v124, v84
	v_add_f32_e32 v84, v126, v240
	v_sub_f32_e32 v240, v158, v92
	v_cvt_pk_bf16_f32 v4, v210, v211
	v_cvt_pk_bf16_f32 v5, v212, v213
	v_cvt_pk_bf16_f32 v6, v214, v215
	v_cvt_pk_bf16_f32 v7, v216, v93
	v_exp_f32_e32 v93, v240
	v_sub_f32_e32 v240, v172, v92
	v_mfma_f32_32x32x16_bf16 v[32:47], v[232:235], v[8:11], v[32:47]
	v_exp_f32_e32 v128, v240
	v_sub_f32_e32 v8, v159, v92
	v_exp_f32_e32 v132, v8
	v_cvt_pk_bf16_f32 v8, v217, v94
	v_cvt_pk_bf16_f32 v9, v95, v96
	ds_read_b128 v[232:235], v99 offset:224
	ds_read_b128 v[236:239], v99 offset:17120
	s_waitcnt lgkmcnt(2)
	v_mfma_f32_32x32x16_bf16 v[16:31], v[0:3], v[4:7], v[16:31]
	v_sub_f32_e32 v240, v157, v92
	v_cvt_pk_bf16_f32 v10, v88, v89
	v_exp_f32_e32 v88, v240
	v_add_f32_e32 v240, v93, v84
	v_add_f32_e32 v240, v128, v240
	v_add_f32_e32 v240, v132, v240
	v_cvt_pk_bf16_f32 v11, v90, v91
	v_mfma_f32_32x32x16_bf16 v[32:47], v[12:15], v[4:7], v[32:47]
	v_add_f32_e32 v84, v88, v240
	v_sub_f32_e32 v4, v156, v92
	v_exp_f32_e32 v89, v4
	v_cvt_pk_bf16_f32 v4, v97, v85
	v_cvt_pk_bf16_f32 v5, v86, v87
	ds_read_b128 v[12:15], v99 offset:256
	ds_read_b128 v[0:3], v99 offset:17152
	s_waitcnt lgkmcnt(2)
	v_mfma_f32_32x32x16_bf16 v[16:31], v[236:239], v[8:11], v[16:31]
	v_sub_f32_e32 v240, v105, v92
	v_exp_f32_e32 v85, v240
	v_sub_f32_e32 v240, v153, v92
	v_exp_f32_e32 v86, v240
	v_sub_f32_e32 v240, v155, v92
	v_cvt_pk_bf16_f32 v6, v122, v124
	v_cvt_pk_bf16_f32 v7, v126, v93
	v_mfma_f32_32x32x16_bf16 v[32:47], v[232:235], v[8:11], v[32:47]
	v_exp_f32_e32 v87, v240
	v_sub_f32_e32 v8, v154, v92
	v_exp_f32_e32 v90, v8
	v_cvt_pk_bf16_f32 v8, v128, v132
	v_cvt_pk_bf16_f32 v9, v88, v89
	ds_read_b128 v[232:235], v99 offset:288
	ds_read_b128 v[236:239], v99 offset:17184
	s_waitcnt lgkmcnt(2)
	v_mfma_f32_32x32x16_bf16 v[16:31], v[0:3], v[4:7], v[16:31]
	v_add_f32_e32 v240, v89, v84
	v_add_f32_e32 v240, v85, v240
	v_cvt_pk_bf16_f32 v10, v85, v86
	v_cvt_pk_bf16_f32 v11, v87, v90
	v_add_f32_e32 v240, v86, v240
	v_add_f32_e32 v240, v87, v240
	v_mfma_f32_32x32x16_bf16 v[32:47], v[12:15], v[4:7], v[32:47]
	v_add_f32_e32 v4, v90, v240
	ds_bpermute_b32 v5, v82, v4
	v_sub_f32_e32 v6, v83, v92
	v_exp_f32_e32 v6, v6
	s_waitcnt vmcnt(3)
	ds_write_b128 v138, v[64:67]
	s_waitcnt vmcnt(2)
	ds_write_b128 v138, v[68:71] offset:1152
	s_waitcnt vmcnt(1)
	ds_write_b128 v138, v[72:75] offset:2304
	s_waitcnt vmcnt(0)
	ds_write_b128 v138, v[76:79] offset:3456
	s_waitcnt lgkmcnt(5)
	v_mfma_f32_32x32x16_bf16 v[32:47], v[232:235], v[8:11], v[32:47]
	s_waitcnt lgkmcnt(4)
; #define LAS __attribute__((address_space(3)))
; __device__ __forceinline__ unsigned pk2(float lo, float hi) { return pg8::cvt_pk_bf16(lo, hi); }
; __device__ __forceinline__ float bflo(unsigned w) { return __uint_as_float(w << 16); }
; __device__ __forceinline__ float bfhi(unsigned w) { return __uint_as_float(w & 0xffff0000u); }
; __device__ __forceinline__ void attn_unit(LAS unsigned char* lds, int unit, int mode, const bf16* QKVG, const float* sinks, const float* gain_a, bf16* MIX, float* SSA) {
;     ...
;         const float inv = __builtin_amdgcn_rcpf(sum);
;         f32x16 ot[2]; ot[0] = f32x16{}; ot[1] = f32x16{};
; #pragma unroll
;         for (int j = 0; j < 5; ++j)
; #pragma unroll
;             for (int s2 = 0; s2 < 2; ++s2) {
;                 v4u pw; pw.x = pk2(st[j][8 * s2 + 0], st[j][8 * s2 + 1]); pw.y = pk2(st[j][8 * s2 + 2], st[j][8 * s2 + 3]);
;                 pw.z = pk2(st[j][8 * s2 + 4], st[j][8 * s2 + 5]); pw.w = pk2(st[j][8 * s2 + 6], st[j][8 * s2 + 7]);
;                 const bf16x8 pf = __builtin_bit_cast(bf16x8, pw);
; #pragma unroll
;                 for (int db = 0; db < 2; ++db) {
;                     const bf16x8 vf = *(const LAS bf16x8*)(Vt + (db * 32 + q) * VP + 32 * (i + j) + 16 * s2 + 8 * hh);
;                     ot[db] = __builtin_amdgcn_mfma_f32_32x32x16_bf16(vf, pf, ot[db], 0, 0, 0);
;                 }
;             }
;         float ss = 0.f;
; #pragma unroll
;         for (int k = 0; k < 4; ++k) *(LAS v4u*)(wt_row + 8 * k * KP) = grow[k];
; #pragma unroll
;         for (int e = 0; e < 8; ++e) gt[e] = *(const LAS v2u*)(wt_frd + 32 * (e >> 2) + 8 * (e & 3));
; #pragma unroll
;         for (int e = 0; e < 8; ++e) {
;             const int db = e >> 2, g4 = e & 3;
;             const float o0 = ot[db][4 * g4 + 0] * inv, o1 = ot[db][4 * g4 + 1] * inv, o2 = ot[db][4 * g4 + 2] * inv, o3 = ot[db][4 * g4 + 3] * inv;
;             ss += (o0 * o0 + o1 * o1) + (o2 * o2 + o3 * o3);
;             const f32x4 gn = *(const LAS f32x4*)(GN + 4 * hh + 32 * db + 8 * g4);
;             v2u z; z.x = pk2(o0 * gn[0] * silu(bflo(gt[e].x)), o1 * gn[1] * silu(bfhi(gt[e].x)));
;             z.y = pk2(o2 * gn[2] * silu(bflo(gt[e].y)), o3 * gn[3] * silu(bfhi(gt[e].y)));
;             *(LAS v2u*)(wt_frd + 32 * db + 8 * g4) = z;
;         }
	v_add_f32_e32 v4, v4, v5
	v_add_f32_e32 v4, v6, v4
	v_rcp_f32_e32 v83, v4
	s_nop 7
	v_mul_f32_e32 v5, v32, v83
	v_mfma_f32_32x32x16_bf16 v[16:31], v[236:239], v[8:11], v[16:31]
	ds_read2_b64 v[6:9], v148 offset1:2
	ds_read2_b64 v[10:13], v148 offset0:4 offset1:6
	ds_read2_b64 v[64:67], v148 offset0:8 offset1:10
	ds_read2_b64 v[0:3], v148 offset0:12 offset1:14
	v_mul_f32_e32 v15, v33, v83
	s_waitcnt lgkmcnt(3)
	v_lshlrev_b32_e32 v4, 16, v6
	v_mul_f32_e32 v14, 0xbfb8aa3b, v4
	v_exp_f32_e32 v68, v14
	v_and_b32_e32 v14, 0xffff0000, v6
	v_mul_f32_e32 v6, 0xbfb8aa3b, v14
	v_mul_f32_e32 v69, v34, v83
	v_mul_f32_e32 v71, v35, v83
	ds_read_b128 v[32:35], v144
	v_exp_f32_e32 v6, v6
	v_add_f32_e32 v68, 1.0, v68
	v_rcp_f32_e32 v72, v68
	v_lshlrev_b32_e32 v68, 16, v7
	v_add_f32_e32 v6, 1.0, v6
	s_waitcnt lgkmcnt(0)
	v_mov_b32_e32 v73, v32
	v_rcp_f32_e32 v32, v6
	v_mul_f32_e32 v6, 0xbfb8aa3b, v68
	v_and_b32_e32 v70, 0xffff0000, v7
	v_mul_f32_e32 v74, v15, v15
	v_pk_mul_f32 v[14:15], v[32:33], v[14:15]
	v_exp_f32_e32 v6, v6
	v_mul_f32_e32 v7, 0xbfb8aa3b, v70
	v_mul_f32_e32 v14, v14, v15
	v_exp_f32_e32 v15, v7
	v_add_f32_e32 v6, 1.0, v6
	v_rcp_f32_e32 v6, v6
	v_mov_b32_e32 v7, v34
	v_add_f32_e32 v15, 1.0, v15
	v_rcp_f32_e32 v34, v15
	v_pk_mul_f32 v[72:73], v[72:73], v[4:5]
	v_pk_mul_f32 v[6:7], v[6:7], v[68:69]
	v_mul_f32_e32 v4, v72, v73
	v_cvt_pk_bf16_f32 v14, v4, v14
	v_mul_f32_e32 v4, v6, v7
	v_pk_mul_f32 v[6:7], v[34:35], v[70:71]
	v_mul_f32_e32 v75, v71, v71
	v_mul_f32_e32 v6, v6, v7
	v_cvt_pk_bf16_f32 v15, v4, v6
	v_lshlrev_b32_e32 v6, 16, v8
	ds_write_b64 v148, v[14:15]
	v_mul_f32_e32 v14, 0xbfb8aa3b, v6
	v_mul_f32_e32 v15, v37, v83
	v_mul_f32_e32 v37, v38, v83
	v_exp_f32_e32 v38, v14
	v_and_b32_e32 v14, 0xffff0000, v8
	v_mul_f32_e32 v8, 0xbfb8aa3b, v14
	ds_read_b128 v[32:35], v144 offset:32
	v_exp_f32_e32 v8, v8
	v_add_f32_e32 v38, 1.0, v38
	v_rcp_f32_e32 v68, v38
	v_fmac_f32_e32 v75, v69, v69
	v_add_f32_e32 v8, 1.0, v8
	s_waitcnt lgkmcnt(0)
	v_mov_b32_e32 v69, v32
	v_rcp_f32_e32 v32, v8
	v_mul_f32_e32 v39, v39, v83
	v_mul_f32_e32 v7, v36, v83
	v_mul_f32_e32 v4, v15, v15
	v_mul_f32_e32 v36, v39, v39
	v_fmac_f32_e32 v4, v7, v7
	v_fmac_f32_e32 v36, v37, v37
	v_pk_mul_f32 v[6:7], v[68:69], v[6:7]
	v_add_f32_e32 v4, v4, v36
	v_mul_f32_e32 v8, v6, v7
	v_pk_mul_f32 v[6:7], v[32:33], v[14:15]
	v_lshlrev_b32_e32 v36, 16, v9
	v_mul_f32_e32 v14, v6, v7
	v_mul_f32_e32 v6, 0xbfb8aa3b, v36
	v_and_b32_e32 v38, 0xffff0000, v9
	v_exp_f32_e32 v6, v6
	v_mul_f32_e32 v7, 0xbfb8aa3b, v38
	v_exp_f32_e32 v9, v7
	v_mov_b32_e32 v7, v34
	v_add_f32_e32 v6, 1.0, v6
	v_rcp_f32_e32 v6, v6
	v_add_f32_e32 v9, 1.0, v9
	v_rcp_f32_e32 v34, v9
	v_cvt_pk_bf16_f32 v8, v8, v14
	v_pk_mul_f32 v[6:7], v[6:7], v[36:37]
	v_lshlrev_b32_e32 v14, 16, v10
	v_mul_f32_e32 v9, v6, v7
	v_pk_mul_f32 v[6:7], v[34:35], v[38:39]
	v_mul_f32_e32 v32, 0xbfb8aa3b, v14
	v_mul_f32_e32 v6, v6, v7
	v_cvt_pk_bf16_f32 v9, v9, v6
	ds_write_b64 v148, v[8:9] offset:16
	v_exp_f32_e32 v38, v32
	v_and_b32_e32 v32, 0xffff0000, v10
	ds_read_b128 v[6:9], v144 offset:64
	v_mul_f32_e32 v10, 0xbfb8aa3b, v32
	v_exp_f32_e32 v10, v10
	v_add_f32_e32 v38, 1.0, v38
	v_rcp_f32_e32 v38, v38
	s_waitcnt lgkmcnt(0)
	v_mov_b32_e32 v39, v6
	v_add_f32_e32 v6, 1.0, v10
	v_rcp_f32_e32 v6, v6
	v_mul_f32_e32 v33, v41, v83
	v_mul_f32_e32 v37, v43, v83
	v_mul_f32_e32 v15, v40, v83
	v_mul_f32_e32 v35, v42, v83
	v_mul_f32_e32 v34, v33, v33
	v_mul_f32_e32 v36, v37, v37
	v_fmac_f32_e32 v34, v15, v15
	v_fmac_f32_e32 v36, v35, v35
	v_add_f32_e32 v40, v34, v36
	v_pk_mul_f32 v[14:15], v[38:39], v[14:15]
	v_pk_mul_f32 v[6:7], v[6:7], v[32:33]
	v_lshlrev_b32_e32 v34, 16, v11
	v_mul_f32_e32 v10, v14, v15
	v_mul_f32_e32 v14, v6, v7
	v_mul_f32_e32 v6, 0xbfb8aa3b, v34
	v_and_b32_e32 v36, 0xffff0000, v11
	v_exp_f32_e32 v6, v6
	v_mul_f32_e32 v7, 0xbfb8aa3b, v36
	v_exp_f32_e32 v11, v7
	v_mov_b32_e32 v7, v8
	v_add_f32_e32 v6, 1.0, v6
	v_rcp_f32_e32 v6, v6
	v_add_f32_e32 v8, 1.0, v11
	v_rcp_f32_e32 v8, v8
	v_cvt_pk_bf16_f32 v10, v10, v14
	v_pk_mul_f32 v[6:7], v[6:7], v[34:35]
	v_mul_f32_e32 v15, v45, v83
	v_mul_f32_e32 v11, v6, v7
	v_pk_mul_f32 v[6:7], v[8:9], v[36:37]
	v_mul_f32_e32 v35, v47, v83
	v_mul_f32_e32 v6, v6, v7
	v_cvt_pk_bf16_f32 v11, v11, v6
	ds_write_b64 v148, v[10:11] offset:32
	v_lshlrev_b32_e32 v10, 16, v12
	v_mul_f32_e32 v14, 0xbfb8aa3b, v10
	v_exp_f32_e32 v36, v14
	v_and_b32_e32 v14, 0xffff0000, v12
	ds_read_b128 v[6:9], v144 offset:96
	v_mul_f32_e32 v12, 0xbfb8aa3b, v14
	v_exp_f32_e32 v12, v12
	v_add_f32_e32 v36, 1.0, v36
	v_rcp_f32_e32 v36, v36
	s_waitcnt lgkmcnt(0)
	v_mov_b32_e32 v37, v6
	v_add_f32_e32 v6, 1.0, v12
	v_rcp_f32_e32 v6, v6
	v_mul_f32_e32 v11, v44, v83
	v_mul_f32_e32 v33, v46, v83
	v_mul_f32_e32 v32, v15, v15
	v_mul_f32_e32 v34, v35, v35
	v_fmac_f32_e32 v32, v11, v11
	v_fmac_f32_e32 v34, v33, v33
	v_add_f32_e32 v38, v32, v34
	v_pk_mul_f32 v[10:11], v[36:37], v[10:11]
	v_pk_mul_f32 v[6:7], v[6:7], v[14:15]
	v_lshlrev_b32_e32 v32, 16, v13
	v_mul_f32_e32 v10, v10, v11
	v_mul_f32_e32 v11, v6, v7
	v_mul_f32_e32 v6, 0xbfb8aa3b, v32
	v_and_b32_e32 v34, 0xffff0000, v13
	v_exp_f32_e32 v6, v6
	v_mul_f32_e32 v7, 0xbfb8aa3b, v34
	v_exp_f32_e32 v12, v7
	v_mov_b32_e32 v7, v8
	v_add_f32_e32 v6, 1.0, v6
	v_rcp_f32_e32 v6, v6
	v_add_f32_e32 v8, 1.0, v12
	v_rcp_f32_e32 v8, v8
	v_cvt_pk_bf16_f32 v10, v10, v11
	v_pk_mul_f32 v[6:7], v[6:7], v[32:33]
	v_mul_f32_e32 v15, v18, v83
	v_mul_f32_e32 v11, v6, v7
	v_pk_mul_f32 v[6:7], v[8:9], v[34:35]
	v_mul_f32_e32 v13, v17, v83
	v_mul_f32_e32 v6, v6, v7
	v_cvt_pk_bf16_f32 v11, v11, v6
	ds_write_b64 v148, v[10:11] offset:48
	v_lshlrev_b32_e32 v10, 16, v64
	v_mul_f32_e32 v12, 0xbfb8aa3b, v10
	v_exp_f32_e32 v18, v12
	v_and_b32_e32 v12, 0xffff0000, v64
	v_mul_f32_e32 v17, v19, v83
	ds_read_b128 v[6:9], v144 offset:128
	v_mul_f32_e32 v19, 0xbfb8aa3b, v12
	v_exp_f32_e32 v32, v19
	v_add_f32_e32 v18, 1.0, v18
	v_rcp_f32_e32 v18, v18
	s_waitcnt lgkmcnt(0)
; #define LAS __attribute__((address_space(3)))
; __device__ __forceinline__ unsigned pk2(float lo, float hi) { return pg8::cvt_pk_bf16(lo, hi); }
; __device__ __forceinline__ float bflo(unsigned w) { return __uint_as_float(w << 16); }
; __device__ __forceinline__ float bfhi(unsigned w) { return __uint_as_float(w & 0xffff0000u); }
; __device__ __forceinline__ float silu(float g) { return g * __builtin_amdgcn_rcpf(1.0f + __builtin_amdgcn_exp2f(-1.4426950408889634f * g)); }
; __device__ __forceinline__ void attn_unit(LAS unsigned char* lds, int unit, int mode, const bf16* QKVG, const float* sinks, const float* gain_a, bf16* MIX, float* SSA) {
;     ...
;         for (int e = 0; e < 8; ++e) gt[e] = *(const LAS v2u*)(wt_frd + 32 * (e >> 2) + 8 * (e & 3));
; #pragma unroll
;         for (int e = 0; e < 8; ++e) {
;             const int db = e >> 2, g4 = e & 3;
;             const float o0 = ot[db][4 * g4 + 0] * inv, o1 = ot[db][4 * g4 + 1] * inv, o2 = ot[db][4 * g4 + 2] * inv, o3 = ot[db][4 * g4 + 3] * inv;
;             ss += (o0 * o0 + o1 * o1) + (o2 * o2 + o3 * o3);
;             const f32x4 gn = *(const LAS f32x4*)(GN + 4 * hh + 32 * db + 8 * g4);
;             v2u z; z.x = pk2(o0 * gn[0] * silu(bflo(gt[e].x)), o1 * gn[1] * silu(bfhi(gt[e].x)));
;             z.y = pk2(o2 * gn[2] * silu(bflo(gt[e].y)), o3 * gn[3] * silu(bfhi(gt[e].y)));
;             *(LAS v2u*)(wt_frd + 32 * db + 8 * g4) = z;
;         }
;         {
;             bf16* orow0 = MIX + (size_t)(T0 + 32 * i + r8) * DMIX + 1024 + h * 64 + 8 * c8;
; #pragma unroll
;             for (int k = 0; k < 4; ++k) { const v4u v = *(const LAS v4u*)(wt_row + 8 * k * KP); *(v4u*)(orow0 + (size_t)(8 * k) * DMIX) = v; }
;         }
; #pragma unroll
;         for (int k = 0; k < 4; ++k) *(LAS v4u*)(wt_row + 8 * k * KP) = qrow[k];
;         ss += __shfl_xor(ss, 32);
;         if (hh == 0) SS[w * 128 + 32 * i + q] = ss;
; #pragma unroll
;         for (int s = 0; s < 4; ++s) qr[s] = *(const LAS bf16x8*)(wt_frq + 16 * s);
;     }
	v_mov_b32_e32 v19, v6
	v_add_f32_e32 v6, 1.0, v32
	v_rcp_f32_e32 v6, v6
	v_mul_f32_e32 v11, v16, v83
	v_mul_f32_e32 v14, v13, v13
	v_mul_f32_e32 v16, v17, v17
	v_fmac_f32_e32 v14, v11, v11
	v_fmac_f32_e32 v16, v15, v15
	v_add_f32_e32 v32, v14, v16
	v_pk_mul_f32 v[10:11], v[18:19], v[10:11]
	v_pk_mul_f32 v[6:7], v[6:7], v[12:13]
	v_lshlrev_b32_e32 v14, 16, v65
	v_mul_f32_e32 v10, v10, v11
	v_mul_f32_e32 v11, v6, v7
	v_mul_f32_e32 v6, 0xbfb8aa3b, v14
	v_and_b32_e32 v16, 0xffff0000, v65
	v_exp_f32_e32 v6, v6
	v_mul_f32_e32 v7, 0xbfb8aa3b, v16
	v_exp_f32_e32 v12, v7
	v_mov_b32_e32 v7, v8
	v_add_f32_e32 v6, 1.0, v6
	v_rcp_f32_e32 v6, v6
	v_add_f32_e32 v8, 1.0, v12
	v_rcp_f32_e32 v8, v8
	v_cvt_pk_bf16_f32 v10, v10, v11
	v_pk_mul_f32 v[6:7], v[6:7], v[14:15]
	v_mul_f32_e32 v13, v21, v83
	v_mul_f32_e32 v11, v6, v7
	v_pk_mul_f32 v[6:7], v[8:9], v[16:17]
	v_mul_f32_e32 v17, v23, v83
	v_mul_f32_e32 v6, v6, v7
	v_cvt_pk_bf16_f32 v11, v11, v6
	ds_write_b64 v148, v[10:11] offset:64
	v_lshlrev_b32_e32 v10, 16, v66
	v_mul_f32_e32 v12, 0xbfb8aa3b, v10
	v_exp_f32_e32 v18, v12
	v_and_b32_e32 v12, 0xffff0000, v66
	ds_read_b128 v[6:9], v144 offset:160
	v_mul_f32_e32 v19, 0xbfb8aa3b, v12
	v_mul_f32_e32 v11, v20, v83
	v_exp_f32_e32 v20, v19
	v_add_f32_e32 v18, 1.0, v18
	s_waitcnt lgkmcnt(0)
	v_mov_b32_e32 v19, v6
	v_rcp_f32_e32 v18, v18
	v_add_f32_e32 v6, 1.0, v20
	v_rcp_f32_e32 v6, v6
	v_mul_f32_e32 v15, v22, v83
	v_mul_f32_e32 v14, v13, v13
	v_mul_f32_e32 v16, v17, v17
	v_fmac_f32_e32 v14, v11, v11
	v_fmac_f32_e32 v16, v15, v15
	v_add_f32_e32 v20, v14, v16
	v_pk_mul_f32 v[10:11], v[18:19], v[10:11]
	v_pk_mul_f32 v[6:7], v[6:7], v[12:13]
	v_lshlrev_b32_e32 v14, 16, v67
	v_mul_f32_e32 v10, v10, v11
	v_mul_f32_e32 v11, v6, v7
	v_mul_f32_e32 v6, 0xbfb8aa3b, v14
	v_and_b32_e32 v16, 0xffff0000, v67
	v_exp_f32_e32 v6, v6
	v_mul_f32_e32 v7, 0xbfb8aa3b, v16
	v_exp_f32_e32 v12, v7
	v_mov_b32_e32 v7, v8
	v_add_f32_e32 v6, 1.0, v6
	v_rcp_f32_e32 v6, v6
	v_add_f32_e32 v8, 1.0, v12
	v_rcp_f32_e32 v8, v8
	v_cvt_pk_bf16_f32 v10, v10, v11
	v_pk_mul_f32 v[6:7], v[6:7], v[14:15]
	v_mul_f32_e32 v13, v25, v83
	v_mul_f32_e32 v11, v6, v7
	v_pk_mul_f32 v[6:7], v[8:9], v[16:17]
	v_mul_f32_e32 v17, v27, v83
	v_mul_f32_e32 v6, v6, v7
	v_cvt_pk_bf16_f32 v11, v11, v6
	ds_write_b64 v148, v[10:11] offset:80
	v_lshlrev_b32_e32 v10, 16, v0
	v_mul_f32_e32 v12, 0xbfb8aa3b, v10
	v_exp_f32_e32 v18, v12
	v_and_b32_e32 v12, 0xffff0000, v0
	v_mul_f32_e32 v0, 0xbfb8aa3b, v12
	ds_read_b128 v[6:9], v144 offset:192
	v_exp_f32_e32 v0, v0
	v_mul_f32_e32 v11, v24, v83
	v_mul_f32_e32 v15, v26, v83
	v_mul_f32_e32 v14, v13, v13
	v_add_f32_e32 v0, 1.0, v0
	v_mul_f32_e32 v16, v17, v17
	s_waitcnt lgkmcnt(0)
	v_mov_b32_e32 v19, v6
	v_rcp_f32_e32 v6, v0
	v_fmac_f32_e32 v14, v11, v11
	v_fmac_f32_e32 v16, v15, v15
	v_add_f32_e32 v21, v14, v16
	v_lshlrev_b32_e32 v14, 16, v1
	v_mul_f32_e32 v0, 0xbfb8aa3b, v14
	v_and_b32_e32 v16, 0xffff0000, v1
	v_pk_mul_f32 v[6:7], v[6:7], v[12:13]
	v_exp_f32_e32 v0, v0
	v_mul_f32_e32 v1, 0xbfb8aa3b, v16
	v_mul_f32_e32 v6, v6, v7
	v_exp_f32_e32 v7, v1
	v_add_f32_e32 v0, 1.0, v0
	v_rcp_f32_e32 v0, v0
	v_add_f32_e32 v18, 1.0, v18
	v_add_f32_e32 v7, 1.0, v7
	v_mov_b32_e32 v1, v8
	v_rcp_f32_e32 v8, v7
	v_rcp_f32_e32 v18, v18
	v_pk_mul_f32 v[0:1], v[0:1], v[14:15]
	v_and_b32_e32 v14, 0xffff0000, v3
	v_mul_f32_e32 v7, v0, v1
	v_pk_mul_f32 v[0:1], v[8:9], v[16:17]
	v_pk_mul_f32 v[10:11], v[18:19], v[10:11]
	v_mul_f32_e32 v0, v0, v1
	v_mul_f32_e32 v10, v10, v11
	v_cvt_pk_bf16_f32 v6, v10, v6
	v_cvt_pk_bf16_f32 v7, v7, v0
	v_lshlrev_b32_e32 v0, 16, v2
	v_mul_f32_e32 v10, 0xbfb8aa3b, v0
	v_exp_f32_e32 v12, v10
	v_and_b32_e32 v10, 0xffff0000, v2
	ds_write_b64 v148, v[6:7] offset:96
	v_mul_f32_e32 v2, 0xbfb8aa3b, v10
	ds_read_b128 v[6:9], v144 offset:224
	v_exp_f32_e32 v2, v2
	v_add_f32_e32 v12, 1.0, v12
	v_rcp_f32_e32 v16, v12
	v_mul_f32_e32 v11, v29, v83
	v_add_f32_e32 v2, 1.0, v2
	s_waitcnt lgkmcnt(0)
	v_mov_b32_e32 v17, v6
	v_rcp_f32_e32 v6, v2
	v_mul_f32_e32 v1, v28, v83
	v_mul_f32_e32 v18, v11, v11
	v_fmac_f32_e32 v18, v1, v1
	v_pk_mul_f32 v[0:1], v[16:17], v[0:1]
	v_lshlrev_b32_e32 v12, 16, v3
	v_mul_f32_e32 v2, v0, v1
	v_pk_mul_f32 v[0:1], v[6:7], v[10:11]
	v_mul_f32_e32 v13, v30, v83
	v_mul_f32_e32 v6, v0, v1
	v_mul_f32_e32 v0, 0xbfb8aa3b, v12
	v_exp_f32_e32 v0, v0
	v_mul_f32_e32 v1, 0xbfb8aa3b, v14
	v_exp_f32_e32 v3, v1
	v_mov_b32_e32 v1, v8
	v_add_f32_e32 v0, 1.0, v0
	v_rcp_f32_e32 v0, v0
	v_add_f32_e32 v3, 1.0, v3
	v_rcp_f32_e32 v8, v3
	v_mul_f32_e32 v15, v31, v83
	v_pk_mul_f32 v[0:1], v[0:1], v[12:13]
	v_mul_f32_e32 v19, v15, v15
	v_mul_f32_e32 v3, v0, v1
	v_pk_mul_f32 v[0:1], v[8:9], v[14:15]
	v_cvt_pk_bf16_f32 v2, v2, v6
	v_fmac_f32_e32 v19, v13, v13
	v_mul_f32_e32 v0, v0, v1
	v_cvt_pk_bf16_f32 v3, v3, v0
	ds_write_b64 v148, v[2:3] offset:112
	ds_read_b128 v[0:3], v138
	ds_read_b128 v[6:9], v138 offset:1152
	ds_read_b128 v[10:13], v138 offset:2304
	ds_read_b128 v[14:17], v138 offset:3456
	v_fmac_f32_e32 v74, v5, v5
	s_waitcnt lgkmcnt(3)
	global_store_dwordx4 v[114:115], v[0:3], off offset:2048
	s_waitcnt lgkmcnt(2)
	global_store_dwordx4 v[116:117], v[6:9], off offset:2048
	s_waitcnt lgkmcnt(1)
	global_store_dwordx4 v[118:119], v[10:13], off offset:2048
	s_waitcnt lgkmcnt(0)
	global_store_dwordx4 v[120:121], v[14:17], off offset:2048
	v_add_f32_e32 v0, v74, v75
	v_add_f32_e32 v0, v0, v4
	v_add_f32_e32 v0, v40, v0
	v_add_f32_e32 v0, v38, v0
	v_add_f32_e32 v0, v32, v0
	v_add_f32_e32 v0, v20, v0
	v_add_f32_e32 v18, v18, v19
	v_add_f32_e32 v0, v21, v0
	v_add_f32_e32 v0, v18, v0
	ds_bpermute_b32 v1, v82, v0
	ds_write_b128 v138, v[48:51]
	ds_write_b128 v138, v[52:55] offset:1152
	ds_write_b128 v138, v[56:59] offset:2304
	ds_write_b128 v138, v[60:63] offset:3456
	s_and_saveexec_b64 s[6:7], s[4:5]
	s_cbranch_execz .LBB0_295
	s_waitcnt lgkmcnt(4)
	v_add_f32_e32 v0, v0, v1
	ds_write_b32 v146, v0
	s_branch .LBB0_295
